# YSET/YADD epilogue rewritten: gate/Y loads of the second row half issued before the first half's stores (2 load round trips instead of 4 store-then-load batches)
# baseline (speedup 1.0000x reference)
; __device__ __forceinline__ unsigned pk2(float lo, float hi) { unsigned r; asm volatile("v_cvt_pk_bf16_f32 %0, %1, %2" : "=v"(r) : "v"(lo), "v"(hi)); return r; }
; __device__ __forceinline__ float bflo(unsigned w) { return __uint_as_float(w << 16); }
; __device__ __forceinline__ float bfhi(unsigned w) { return __uint_as_float(w & 0xffff0000u); }
; #define GAS __attribute__((address_space(1)))
; __device__ __forceinline__ void gemm_epilogue(LAS unsigned char* lds, const GD& gd, const f32x4 (&acc)[2][2][4][2], const Unit& u) {
;     ...
;     if (mode == M_YSET || mode == M_YADD) {
; #pragma unroll
;         for (int am = 0; am < 8 / MBG; ++am) {
;             const int ai = (am * MBG) >> 2, m0 = (am * MBG) & 3;
;             u32x4 gw[MBG][2], yw[MBG][2];
; #pragma unroll
;             for (int mm = 0; mm < MBG; ++mm)
; #pragma unroll
;                 for (int bj = 0; bj < 2; ++bj) {
;                     const int ro = ai * HALF + (m0 + mm) * 16;
;                     gw[mm][bj] = *(GAS const u32x4*)(auxu + goff + ro * apitch + bj * HALF);
;                     if (mode == M_YADD) yw[mm][bj] = *(GAS const u32x4*)(outu + ooff + ro * ldc + bj * HALF);
;                 }
;             asm volatile("" ::: "memory");
; #pragma unroll
;             for (int mm = 0; mm < MBG; ++mm) {
;                 const int m = m0 + mm;
; #pragma unroll
;                 for (int bj = 0; bj < 2; ++bj) {
;                     f32x4 v0 = acc[ai][bj][m][0], v1 = acc[ai][bj][m][1];
;                     const u32x4 q = gw[mm][bj];
;                     v0[0] *= bflo(q.x); v0[1] *= bfhi(q.x); v0[2] *= bflo(q.y); v0[3] *= bfhi(q.y);
;                     v1[0] *= bflo(q.z); v1[1] *= bfhi(q.z); v1[2] *= bflo(q.w); v1[3] *= bfhi(q.w);
;                     if (mode == M_YADD) {
;                         const u32x4 y = yw[mm][bj];
;                         v0[0] += bflo(y.x); v0[1] += bfhi(y.x); v0[2] += bflo(y.y); v0[3] += bfhi(y.y);
;                         v1[0] += bflo(y.z); v1[1] += bfhi(y.z); v1[2] += bflo(y.w); v1[3] += bfhi(y.w);
;                     }
;                     u32x4 w; w.x = pk2(v0[0], v0[1]); w.y = pk2(v0[2], v0[3]); w.z = pk2(v1[0], v1[1]); w.w = pk2(v1[2], v1[3]);
;                     *(GAS u32x4*)(outu + ooff + (ai * HALF + m * 16) * ldc + bj * HALF) = w;
;                 }
;             }
;         }
;         return;
;     }
.LBB0_555:
	s_and_b64 vcc, exec, s[6:7]
	s_cbranch_vccz .LBB0_621
	s_and_b64 s[6:7], s[94:95], exec
	s_movk_i32 s2, 0xc00
	s_cselect_b32 s6, s2, 0x400
	v_mul_lo_u32 v132, v174, s6
	v_or_b32_e32 v96, v132, v96
	v_lshlrev_b32_e32 v202, 1, v96
	v_lshlrev_b32_e32 v203, 1, v156
	s_lshl_b32 s2, s6, 5
	s_lshl_b32 s7, s90, 5
	s_lshl_b32 s44, s2, 2
	s_lshl_b32 s45, s7, 2
	s_mov_b64 s[46:47], s[96:97]
	s_mov_b64 s[48:49], s[92:93]
	s_mov_b64 s[50:51], s[92:93]
	s_cmp_eq_u32 s78, 4
	s_cbranch_scc1 .Lmy_yadd
	global_load_dwordx4 v[130:133], v202, s[46:47]
	global_load_dwordx4 v[134:137], v202, s[46:47] offset:256
	s_add_u32 s46, s46, s2
	s_addc_u32 s47, s47, 0
	global_load_dwordx4 v[138:141], v202, s[46:47]
	global_load_dwordx4 v[142:145], v202, s[46:47] offset:256
	s_add_u32 s46, s46, s2
	s_addc_u32 s47, s47, 0
	global_load_dwordx4 v[146:149], v202, s[46:47]
	global_load_dwordx4 v[150:153], v202, s[46:47] offset:256
	s_add_u32 s46, s46, s2
	s_addc_u32 s47, s47, 0
	global_load_dwordx4 v[154:157], v202, s[46:47]
	global_load_dwordx4 v[158:161], v202, s[46:47] offset:256
	s_add_u32 s46, s46, s2
	s_addc_u32 s47, s47, 0
	s_add_u32 s46, s46, s44
	s_addc_u32 s47, s47, 0
	s_waitcnt vmcnt(0)
	v_lshlrev_b32_e32 v194, 16, v130
	v_and_b32_e32 v195, 0xffff0000, v130
	v_pk_mul_f32 v[126:127], v[126:127], v[194:195]
	v_lshlrev_b32_e32 v196, 16, v131
	v_and_b32_e32 v197, 0xffff0000, v131
	v_pk_mul_f32 v[128:129], v[128:129], v[196:197]
	v_lshlrev_b32_e32 v198, 16, v132
	v_and_b32_e32 v199, 0xffff0000, v132
	v_pk_mul_f32 v[4:5], v[4:5], v[198:199]
	v_lshlrev_b32_e32 v200, 16, v133
	v_and_b32_e32 v201, 0xffff0000, v133
	v_pk_mul_f32 v[6:7], v[6:7], v[200:201]
	v_cvt_pk_bf16_f32 v126, v126, v127
	v_cvt_pk_bf16_f32 v127, v128, v129
	v_cvt_pk_bf16_f32 v128, v4, v5
	v_cvt_pk_bf16_f32 v129, v6, v7
	v_lshlrev_b32_e32 v194, 16, v134
	v_and_b32_e32 v195, 0xffff0000, v134
	v_pk_mul_f32 v[48:49], v[48:49], v[194:195]
	v_lshlrev_b32_e32 v196, 16, v135
	v_and_b32_e32 v197, 0xffff0000, v135
	v_pk_mul_f32 v[50:51], v[50:51], v[196:197]
	v_lshlrev_b32_e32 v198, 16, v136
	v_and_b32_e32 v199, 0xffff0000, v136
	v_pk_mul_f32 v[12:13], v[12:13], v[198:199]
	v_lshlrev_b32_e32 v200, 16, v137
	v_and_b32_e32 v201, 0xffff0000, v137
	v_pk_mul_f32 v[14:15], v[14:15], v[200:201]
	v_cvt_pk_bf16_f32 v48, v48, v49
	v_cvt_pk_bf16_f32 v49, v50, v51
	v_cvt_pk_bf16_f32 v50, v12, v13
	v_cvt_pk_bf16_f32 v51, v14, v15
	v_lshlrev_b32_e32 v194, 16, v138
	v_and_b32_e32 v195, 0xffff0000, v138
	v_pk_mul_f32 v[122:123], v[122:123], v[194:195]
	v_lshlrev_b32_e32 v196, 16, v139
	v_and_b32_e32 v197, 0xffff0000, v139
	v_pk_mul_f32 v[124:125], v[124:125], v[196:197]
	v_lshlrev_b32_e32 v198, 16, v140
	v_and_b32_e32 v199, 0xffff0000, v140
	v_pk_mul_f32 v[118:119], v[118:119], v[198:199]
	v_lshlrev_b32_e32 v200, 16, v141
	v_and_b32_e32 v201, 0xffff0000, v141
	v_pk_mul_f32 v[120:121], v[120:121], v[200:201]
	v_cvt_pk_bf16_f32 v122, v122, v123
	v_cvt_pk_bf16_f32 v123, v124, v125
	v_cvt_pk_bf16_f32 v124, v118, v119
	v_cvt_pk_bf16_f32 v125, v120, v121
	v_lshlrev_b32_e32 v194, 16, v142
	v_and_b32_e32 v195, 0xffff0000, v142
	v_pk_mul_f32 v[102:103], v[102:103], v[194:195]
	v_lshlrev_b32_e32 v196, 16, v143
	v_and_b32_e32 v197, 0xffff0000, v143
	v_pk_mul_f32 v[104:105], v[104:105], v[196:197]
	v_lshlrev_b32_e32 v198, 16, v144
	v_and_b32_e32 v199, 0xffff0000, v144
	v_pk_mul_f32 v[98:99], v[98:99], v[198:199]
	v_lshlrev_b32_e32 v200, 16, v145
	v_and_b32_e32 v201, 0xffff0000, v145
	v_pk_mul_f32 v[100:101], v[100:101], v[200:201]
	v_cvt_pk_bf16_f32 v102, v102, v103
	v_cvt_pk_bf16_f32 v103, v104, v105
	v_cvt_pk_bf16_f32 v104, v98, v99
	v_cvt_pk_bf16_f32 v105, v100, v101
	v_lshlrev_b32_e32 v194, 16, v146
	v_and_b32_e32 v195, 0xffff0000, v146
	v_pk_mul_f32 v[114:115], v[114:115], v[194:195]
	v_lshlrev_b32_e32 v196, 16, v147
	v_and_b32_e32 v197, 0xffff0000, v147
	v_pk_mul_f32 v[116:117], v[116:117], v[196:197]
	v_lshlrev_b32_e32 v198, 16, v148
	v_and_b32_e32 v199, 0xffff0000, v148
	v_pk_mul_f32 v[110:111], v[110:111], v[198:199]
	v_lshlrev_b32_e32 v200, 16, v149
	v_and_b32_e32 v201, 0xffff0000, v149
	v_pk_mul_f32 v[112:113], v[112:113], v[200:201]
	v_cvt_pk_bf16_f32 v114, v114, v115
	v_cvt_pk_bf16_f32 v115, v116, v117
	v_cvt_pk_bf16_f32 v116, v110, v111
	v_cvt_pk_bf16_f32 v117, v112, v113
	v_lshlrev_b32_e32 v194, 16, v150
	v_and_b32_e32 v195, 0xffff0000, v150
	v_pk_mul_f32 v[92:93], v[92:93], v[194:195]
	v_lshlrev_b32_e32 v196, 16, v151
	v_and_b32_e32 v197, 0xffff0000, v151
	v_pk_mul_f32 v[94:95], v[94:95], v[196:197]
	v_lshlrev_b32_e32 v198, 16, v152
	v_and_b32_e32 v199, 0xffff0000, v152
	v_pk_mul_f32 v[88:89], v[88:89], v[198:199]
	v_lshlrev_b32_e32 v200, 16, v153
	v_and_b32_e32 v201, 0xffff0000, v153
	v_pk_mul_f32 v[90:91], v[90:91], v[200:201]
	v_cvt_pk_bf16_f32 v92, v92, v93
	v_cvt_pk_bf16_f32 v93, v94, v95
	v_cvt_pk_bf16_f32 v94, v88, v89
	v_cvt_pk_bf16_f32 v95, v90, v91
	v_lshlrev_b32_e32 v194, 16, v154
	v_and_b32_e32 v195, 0xffff0000, v154
	v_pk_mul_f32 v[106:107], v[106:107], v[194:195]
	v_lshlrev_b32_e32 v196, 16, v155
	v_and_b32_e32 v197, 0xffff0000, v155
	v_pk_mul_f32 v[108:109], v[108:109], v[196:197]
	v_lshlrev_b32_e32 v198, 16, v156
	v_and_b32_e32 v199, 0xffff0000, v156
	v_pk_mul_f32 v[8:9], v[8:9], v[198:199]
	v_lshlrev_b32_e32 v200, 16, v157
	v_and_b32_e32 v201, 0xffff0000, v157
	v_pk_mul_f32 v[10:11], v[10:11], v[200:201]
	v_cvt_pk_bf16_f32 v106, v106, v107
	v_cvt_pk_bf16_f32 v107, v108, v109
	v_cvt_pk_bf16_f32 v108, v8, v9
	v_cvt_pk_bf16_f32 v109, v10, v11
	v_lshlrev_b32_e32 v194, 16, v158
	v_and_b32_e32 v195, 0xffff0000, v158
	v_pk_mul_f32 v[44:45], v[44:45], v[194:195]
	v_lshlrev_b32_e32 v196, 16, v159
; __device__ __forceinline__ unsigned pk2(float lo, float hi) { unsigned r; asm volatile("v_cvt_pk_bf16_f32 %0, %1, %2" : "=v"(r) : "v"(lo), "v"(hi)); return r; }
; __device__ __forceinline__ float bflo(unsigned w) { return __uint_as_float(w << 16); }
; __device__ __forceinline__ float bfhi(unsigned w) { return __uint_as_float(w & 0xffff0000u); }
; #define GAS __attribute__((address_space(1)))
; __device__ __forceinline__ void gemm_epilogue(LAS unsigned char* lds, const GD& gd, const f32x4 (&acc)[2][2][4][2], const Unit& u) {
;     ...
;     if (mode == M_YSET || mode == M_YADD) {
; #pragma unroll
;         for (int am = 0; am < 8 / MBG; ++am) {
;             const int ai = (am * MBG) >> 2, m0 = (am * MBG) & 3;
;             u32x4 gw[MBG][2], yw[MBG][2];
; #pragma unroll
;             for (int mm = 0; mm < MBG; ++mm)
; #pragma unroll
;                 for (int bj = 0; bj < 2; ++bj) {
;                     const int ro = ai * HALF + (m0 + mm) * 16;
;                     gw[mm][bj] = *(GAS const u32x4*)(auxu + goff + ro * apitch + bj * HALF);
;                     if (mode == M_YADD) yw[mm][bj] = *(GAS const u32x4*)(outu + ooff + ro * ldc + bj * HALF);
;                 }
;             asm volatile("" ::: "memory");
; #pragma unroll
;             for (int mm = 0; mm < MBG; ++mm) {
;                 const int m = m0 + mm;
; #pragma unroll
;                 for (int bj = 0; bj < 2; ++bj) {
;                     f32x4 v0 = acc[ai][bj][m][0], v1 = acc[ai][bj][m][1];
;                     const u32x4 q = gw[mm][bj];
;                     v0[0] *= bflo(q.x); v0[1] *= bfhi(q.x); v0[2] *= bflo(q.y); v0[3] *= bfhi(q.y);
;                     v1[0] *= bflo(q.z); v1[1] *= bfhi(q.z); v1[2] *= bflo(q.w); v1[3] *= bfhi(q.w);
;                     if (mode == M_YADD) {
;                         const u32x4 y = yw[mm][bj];
;                         v0[0] += bflo(y.x); v0[1] += bfhi(y.x); v0[2] += bflo(y.y); v0[3] += bfhi(y.y);
;                         v1[0] += bflo(y.z); v1[1] += bfhi(y.z); v1[2] += bflo(y.w); v1[3] += bfhi(y.w);
;                     }
;                     u32x4 w; w.x = pk2(v0[0], v0[1]); w.y = pk2(v0[2], v0[3]); w.z = pk2(v1[0], v1[1]); w.w = pk2(v1[2], v1[3]);
;                     *(GAS u32x4*)(outu + ooff + (ai * HALF + m * 16) * ldc + bj * HALF) = w;
;                 }
;             }
;         }
;         return;
;     }
	v_and_b32_e32 v197, 0xffff0000, v159
	v_pk_mul_f32 v[46:47], v[46:47], v[196:197]
	v_lshlrev_b32_e32 v198, 16, v160
	v_and_b32_e32 v199, 0xffff0000, v160
	v_pk_mul_f32 v[16:17], v[16:17], v[198:199]
	v_lshlrev_b32_e32 v200, 16, v161
	v_and_b32_e32 v201, 0xffff0000, v161
	v_pk_mul_f32 v[18:19], v[18:19], v[200:201]
	v_cvt_pk_bf16_f32 v44, v44, v45
	v_cvt_pk_bf16_f32 v45, v46, v47
	v_cvt_pk_bf16_f32 v46, v16, v17
	v_cvt_pk_bf16_f32 v47, v18, v19
	global_load_dwordx4 v[130:133], v202, s[46:47]
	global_load_dwordx4 v[134:137], v202, s[46:47] offset:256
	s_add_u32 s46, s46, s2
	s_addc_u32 s47, s47, 0
	global_load_dwordx4 v[138:141], v202, s[46:47]
	global_load_dwordx4 v[142:145], v202, s[46:47] offset:256
	s_add_u32 s46, s46, s2
	s_addc_u32 s47, s47, 0
	global_load_dwordx4 v[146:149], v202, s[46:47]
	global_load_dwordx4 v[150:153], v202, s[46:47] offset:256
	s_add_u32 s46, s46, s2
	s_addc_u32 s47, s47, 0
	global_load_dwordx4 v[154:157], v202, s[46:47]
	global_load_dwordx4 v[158:161], v202, s[46:47] offset:256
	s_add_u32 s46, s46, s2
	s_addc_u32 s47, s47, 0
	global_store_dwordx4 v203, v[126:129], s[50:51]
	global_store_dwordx4 v203, v[48:51], s[50:51] offset:256
	s_add_u32 s50, s50, s7
	s_addc_u32 s51, s51, 0
	global_store_dwordx4 v203, v[122:125], s[50:51]
	global_store_dwordx4 v203, v[102:105], s[50:51] offset:256
	s_add_u32 s50, s50, s7
	s_addc_u32 s51, s51, 0
	global_store_dwordx4 v203, v[114:117], s[50:51]
	global_store_dwordx4 v203, v[92:95], s[50:51] offset:256
	s_add_u32 s50, s50, s7
	s_addc_u32 s51, s51, 0
	global_store_dwordx4 v203, v[106:109], s[50:51]
	global_store_dwordx4 v203, v[44:47], s[50:51] offset:256
	s_add_u32 s50, s50, s7
	s_addc_u32 s51, s51, 0
	s_add_u32 s50, s50, s45
	s_addc_u32 s51, s51, 0
	s_waitcnt vmcnt(8)
	v_lshlrev_b32_e32 v194, 16, v130
	v_and_b32_e32 v195, 0xffff0000, v130
	v_pk_mul_f32 v[84:85], v[84:85], v[194:195]
	v_lshlrev_b32_e32 v196, 16, v131
	v_and_b32_e32 v197, 0xffff0000, v131
	v_pk_mul_f32 v[86:87], v[86:87], v[196:197]
	v_lshlrev_b32_e32 v198, 16, v132
	v_and_b32_e32 v199, 0xffff0000, v132
	v_pk_mul_f32 v[20:21], v[20:21], v[198:199]
	v_lshlrev_b32_e32 v200, 16, v133
	v_and_b32_e32 v201, 0xffff0000, v133
	v_pk_mul_f32 v[22:23], v[22:23], v[200:201]
	v_cvt_pk_bf16_f32 v84, v84, v85
	v_cvt_pk_bf16_f32 v85, v86, v87
	v_cvt_pk_bf16_f32 v86, v20, v21
	v_cvt_pk_bf16_f32 v87, v22, v23
	v_lshlrev_b32_e32 v194, 16, v134
	v_and_b32_e32 v195, 0xffff0000, v134
	v_pk_mul_f32 v[40:41], v[40:41], v[194:195]
	v_lshlrev_b32_e32 v196, 16, v135
	v_and_b32_e32 v197, 0xffff0000, v135
	v_pk_mul_f32 v[42:43], v[42:43], v[196:197]
	v_lshlrev_b32_e32 v198, 16, v136
	v_and_b32_e32 v199, 0xffff0000, v136
	v_pk_mul_f32 v[28:29], v[28:29], v[198:199]
	v_lshlrev_b32_e32 v200, 16, v137
	v_and_b32_e32 v201, 0xffff0000, v137
	v_pk_mul_f32 v[30:31], v[30:31], v[200:201]
	v_cvt_pk_bf16_f32 v40, v40, v41
	v_cvt_pk_bf16_f32 v41, v42, v43
	v_cvt_pk_bf16_f32 v42, v28, v29
	v_cvt_pk_bf16_f32 v43, v30, v31
	v_lshlrev_b32_e32 v194, 16, v138
	v_and_b32_e32 v195, 0xffff0000, v138
	v_pk_mul_f32 v[80:81], v[80:81], v[194:195]
	v_lshlrev_b32_e32 v196, 16, v139
	v_and_b32_e32 v197, 0xffff0000, v139
	v_pk_mul_f32 v[82:83], v[82:83], v[196:197]
	v_lshlrev_b32_e32 v198, 16, v140
	v_and_b32_e32 v199, 0xffff0000, v140
	v_pk_mul_f32 v[76:77], v[76:77], v[198:199]
	v_lshlrev_b32_e32 v200, 16, v141
	v_and_b32_e32 v201, 0xffff0000, v141
	v_pk_mul_f32 v[78:79], v[78:79], v[200:201]
	v_cvt_pk_bf16_f32 v80, v80, v81
	v_cvt_pk_bf16_f32 v81, v82, v83
	v_cvt_pk_bf16_f32 v82, v76, v77
	v_cvt_pk_bf16_f32 v83, v78, v79
	v_lshlrev_b32_e32 v194, 16, v142
	v_and_b32_e32 v195, 0xffff0000, v142
	v_pk_mul_f32 v[60:61], v[60:61], v[194:195]
	v_lshlrev_b32_e32 v196, 16, v143
	v_and_b32_e32 v197, 0xffff0000, v143
	v_pk_mul_f32 v[62:63], v[62:63], v[196:197]
	v_lshlrev_b32_e32 v198, 16, v144
	v_and_b32_e32 v199, 0xffff0000, v144
	v_pk_mul_f32 v[56:57], v[56:57], v[198:199]
	v_lshlrev_b32_e32 v200, 16, v145
	v_and_b32_e32 v201, 0xffff0000, v145
	v_pk_mul_f32 v[58:59], v[58:59], v[200:201]
	v_cvt_pk_bf16_f32 v60, v60, v61
	v_cvt_pk_bf16_f32 v61, v62, v63
	v_cvt_pk_bf16_f32 v62, v56, v57
	v_cvt_pk_bf16_f32 v63, v58, v59
	v_lshlrev_b32_e32 v194, 16, v146
	v_and_b32_e32 v195, 0xffff0000, v146
	v_pk_mul_f32 v[72:73], v[72:73], v[194:195]
	v_lshlrev_b32_e32 v196, 16, v147
	v_and_b32_e32 v197, 0xffff0000, v147
	v_pk_mul_f32 v[74:75], v[74:75], v[196:197]
	v_lshlrev_b32_e32 v198, 16, v148
	v_and_b32_e32 v199, 0xffff0000, v148
	v_pk_mul_f32 v[68:69], v[68:69], v[198:199]
	v_lshlrev_b32_e32 v200, 16, v149
	v_and_b32_e32 v201, 0xffff0000, v149
	v_pk_mul_f32 v[70:71], v[70:71], v[200:201]
	v_cvt_pk_bf16_f32 v72, v72, v73
	v_cvt_pk_bf16_f32 v73, v74, v75
	v_cvt_pk_bf16_f32 v74, v68, v69
	v_cvt_pk_bf16_f32 v75, v70, v71
	v_lshlrev_b32_e32 v194, 16, v150
	v_and_b32_e32 v195, 0xffff0000, v150
	v_pk_mul_f32 v[52:53], v[52:53], v[194:195]
	v_lshlrev_b32_e32 v196, 16, v151
	v_and_b32_e32 v197, 0xffff0000, v151
	v_pk_mul_f32 v[54:55], v[54:55], v[196:197]
	v_lshlrev_b32_e32 v198, 16, v152
	v_and_b32_e32 v199, 0xffff0000, v152
	v_pk_mul_f32 v[0:1], v[0:1], v[198:199]
	v_lshlrev_b32_e32 v200, 16, v153
	v_and_b32_e32 v201, 0xffff0000, v153
	v_pk_mul_f32 v[2:3], v[2:3], v[200:201]
	v_cvt_pk_bf16_f32 v52, v52, v53
	v_cvt_pk_bf16_f32 v53, v54, v55
	v_cvt_pk_bf16_f32 v54, v0, v1
	v_cvt_pk_bf16_f32 v55, v2, v3
	v_lshlrev_b32_e32 v194, 16, v154
	v_and_b32_e32 v195, 0xffff0000, v154
	v_pk_mul_f32 v[64:65], v[64:65], v[194:195]
	v_lshlrev_b32_e32 v196, 16, v155
	v_and_b32_e32 v197, 0xffff0000, v155
	v_pk_mul_f32 v[66:67], v[66:67], v[196:197]
	v_lshlrev_b32_e32 v198, 16, v156
	v_and_b32_e32 v199, 0xffff0000, v156
; __device__ __forceinline__ unsigned pk2(float lo, float hi) { unsigned r; asm volatile("v_cvt_pk_bf16_f32 %0, %1, %2" : "=v"(r) : "v"(lo), "v"(hi)); return r; }
; __device__ __forceinline__ float bflo(unsigned w) { return __uint_as_float(w << 16); }
; __device__ __forceinline__ float bfhi(unsigned w) { return __uint_as_float(w & 0xffff0000u); }
; #define GAS __attribute__((address_space(1)))
; __device__ __forceinline__ void gemm_epilogue(LAS unsigned char* lds, const GD& gd, const f32x4 (&acc)[2][2][4][2], const Unit& u) {
;     ...
;     if (mode == M_YSET || mode == M_YADD) {
; #pragma unroll
;         for (int am = 0; am < 8 / MBG; ++am) {
;             const int ai = (am * MBG) >> 2, m0 = (am * MBG) & 3;
;             u32x4 gw[MBG][2], yw[MBG][2];
; #pragma unroll
;             for (int mm = 0; mm < MBG; ++mm)
; #pragma unroll
;                 for (int bj = 0; bj < 2; ++bj) {
;                     const int ro = ai * HALF + (m0 + mm) * 16;
;                     gw[mm][bj] = *(GAS const u32x4*)(auxu + goff + ro * apitch + bj * HALF);
;                     if (mode == M_YADD) yw[mm][bj] = *(GAS const u32x4*)(outu + ooff + ro * ldc + bj * HALF);
;                 }
;             asm volatile("" ::: "memory");
; #pragma unroll
;             for (int mm = 0; mm < MBG; ++mm) {
;                 const int m = m0 + mm;
; #pragma unroll
;                 for (int bj = 0; bj < 2; ++bj) {
;                     f32x4 v0 = acc[ai][bj][m][0], v1 = acc[ai][bj][m][1];
;                     const u32x4 q = gw[mm][bj];
;                     v0[0] *= bflo(q.x); v0[1] *= bfhi(q.x); v0[2] *= bflo(q.y); v0[3] *= bfhi(q.y);
;                     v1[0] *= bflo(q.z); v1[1] *= bfhi(q.z); v1[2] *= bflo(q.w); v1[3] *= bfhi(q.w);
;                     if (mode == M_YADD) {
;                         const u32x4 y = yw[mm][bj];
;                         v0[0] += bflo(y.x); v0[1] += bfhi(y.x); v0[2] += bflo(y.y); v0[3] += bfhi(y.y);
;                         v1[0] += bflo(y.z); v1[1] += bfhi(y.z); v1[2] += bflo(y.w); v1[3] += bfhi(y.w);
;                     }
;                     u32x4 w; w.x = pk2(v0[0], v0[1]); w.y = pk2(v0[2], v0[3]); w.z = pk2(v1[0], v1[1]); w.w = pk2(v1[2], v1[3]);
;                     *(GAS u32x4*)(outu + ooff + (ai * HALF + m * 16) * ldc + bj * HALF) = w;
;                 }
;             }
;         }
;         return;
;     }
	v_pk_mul_f32 v[24:25], v[24:25], v[198:199]
	v_lshlrev_b32_e32 v200, 16, v157
	v_and_b32_e32 v201, 0xffff0000, v157
	v_pk_mul_f32 v[26:27], v[26:27], v[200:201]
	v_cvt_pk_bf16_f32 v64, v64, v65
	v_cvt_pk_bf16_f32 v65, v66, v67
	v_cvt_pk_bf16_f32 v66, v24, v25
	v_cvt_pk_bf16_f32 v67, v26, v27
	v_lshlrev_b32_e32 v194, 16, v158
	v_and_b32_e32 v195, 0xffff0000, v158
	v_pk_mul_f32 v[36:37], v[36:37], v[194:195]
	v_lshlrev_b32_e32 v196, 16, v159
	v_and_b32_e32 v197, 0xffff0000, v159
	v_pk_mul_f32 v[38:39], v[38:39], v[196:197]
	v_lshlrev_b32_e32 v198, 16, v160
	v_and_b32_e32 v199, 0xffff0000, v160
	v_pk_mul_f32 v[32:33], v[32:33], v[198:199]
	v_lshlrev_b32_e32 v200, 16, v161
	v_and_b32_e32 v201, 0xffff0000, v161
	v_pk_mul_f32 v[34:35], v[34:35], v[200:201]
	v_cvt_pk_bf16_f32 v36, v36, v37
	v_cvt_pk_bf16_f32 v37, v38, v39
	v_cvt_pk_bf16_f32 v38, v32, v33
	v_cvt_pk_bf16_f32 v39, v34, v35
	global_store_dwordx4 v203, v[84:87], s[50:51]
	global_store_dwordx4 v203, v[40:43], s[50:51] offset:256
	s_add_u32 s50, s50, s7
	s_addc_u32 s51, s51, 0
	global_store_dwordx4 v203, v[80:83], s[50:51]
	global_store_dwordx4 v203, v[60:63], s[50:51] offset:256
	s_add_u32 s50, s50, s7
	s_addc_u32 s51, s51, 0
	global_store_dwordx4 v203, v[72:75], s[50:51]
	global_store_dwordx4 v203, v[52:55], s[50:51] offset:256
	s_add_u32 s50, s50, s7
	s_addc_u32 s51, s51, 0
	global_store_dwordx4 v203, v[64:67], s[50:51]
	global_store_dwordx4 v203, v[36:39], s[50:51] offset:256
	s_add_u32 s50, s50, s7
	s_addc_u32 s51, s51, 0
	s_branch .LBB0_621
.Lmy_yadd:
	global_load_dwordx4 v[130:133], v202, s[46:47]
	global_load_dwordx4 v[134:137], v202, s[46:47] offset:256
	global_load_dwordx4 v[162:165], v203, s[48:49]
	global_load_dwordx4 v[166:169], v203, s[48:49] offset:256
	s_add_u32 s46, s46, s2
	s_addc_u32 s47, s47, 0
	s_add_u32 s48, s48, s7
	s_addc_u32 s49, s49, 0
	global_load_dwordx4 v[138:141], v202, s[46:47]
	global_load_dwordx4 v[142:145], v202, s[46:47] offset:256
	global_load_dwordx4 v[170:173], v203, s[48:49]
	global_load_dwordx4 v[174:177], v203, s[48:49] offset:256
	s_add_u32 s46, s46, s2
	s_addc_u32 s47, s47, 0
	s_add_u32 s48, s48, s7
	s_addc_u32 s49, s49, 0
	global_load_dwordx4 v[146:149], v202, s[46:47]
	global_load_dwordx4 v[150:153], v202, s[46:47] offset:256
	global_load_dwordx4 v[178:181], v203, s[48:49]
	global_load_dwordx4 v[182:185], v203, s[48:49] offset:256
	s_add_u32 s46, s46, s2
	s_addc_u32 s47, s47, 0
	s_add_u32 s48, s48, s7
	s_addc_u32 s49, s49, 0
	global_load_dwordx4 v[154:157], v202, s[46:47]
	global_load_dwordx4 v[158:161], v202, s[46:47] offset:256
	global_load_dwordx4 v[186:189], v203, s[48:49]
	global_load_dwordx4 v[190:193], v203, s[48:49] offset:256
	s_add_u32 s46, s46, s2
	s_addc_u32 s47, s47, 0
	s_add_u32 s48, s48, s7
	s_addc_u32 s49, s49, 0
	s_add_u32 s46, s46, s44
	s_addc_u32 s47, s47, 0
	s_add_u32 s48, s48, s45
	s_addc_u32 s49, s49, 0
	s_waitcnt vmcnt(0)
	v_lshlrev_b32_e32 v194, 16, v130
	v_and_b32_e32 v195, 0xffff0000, v130
	v_pk_mul_f32 v[126:127], v[126:127], v[194:195]
	v_lshlrev_b32_e32 v196, 16, v131
	v_and_b32_e32 v197, 0xffff0000, v131
	v_pk_mul_f32 v[128:129], v[128:129], v[196:197]
	v_lshlrev_b32_e32 v198, 16, v132
	v_and_b32_e32 v199, 0xffff0000, v132
	v_pk_mul_f32 v[4:5], v[4:5], v[198:199]
	v_lshlrev_b32_e32 v200, 16, v133
	v_and_b32_e32 v201, 0xffff0000, v133
	v_pk_mul_f32 v[6:7], v[6:7], v[200:201]
	v_lshlrev_b32_e32 v194, 16, v162
	v_and_b32_e32 v195, 0xffff0000, v162
	v_pk_add_f32 v[126:127], v[126:127], v[194:195]
	v_lshlrev_b32_e32 v196, 16, v163
	v_and_b32_e32 v197, 0xffff0000, v163
	v_pk_add_f32 v[128:129], v[128:129], v[196:197]
	v_lshlrev_b32_e32 v198, 16, v164
	v_and_b32_e32 v199, 0xffff0000, v164
	v_pk_add_f32 v[4:5], v[4:5], v[198:199]
	v_lshlrev_b32_e32 v200, 16, v165
	v_and_b32_e32 v201, 0xffff0000, v165
	v_pk_add_f32 v[6:7], v[6:7], v[200:201]
	v_cvt_pk_bf16_f32 v126, v126, v127
	v_cvt_pk_bf16_f32 v127, v128, v129
	v_cvt_pk_bf16_f32 v128, v4, v5
	v_cvt_pk_bf16_f32 v129, v6, v7
	v_lshlrev_b32_e32 v194, 16, v134
	v_and_b32_e32 v195, 0xffff0000, v134
	v_pk_mul_f32 v[48:49], v[48:49], v[194:195]
	v_lshlrev_b32_e32 v196, 16, v135
	v_and_b32_e32 v197, 0xffff0000, v135
	v_pk_mul_f32 v[50:51], v[50:51], v[196:197]
	v_lshlrev_b32_e32 v198, 16, v136
	v_and_b32_e32 v199, 0xffff0000, v136
	v_pk_mul_f32 v[12:13], v[12:13], v[198:199]
	v_lshlrev_b32_e32 v200, 16, v137
	v_and_b32_e32 v201, 0xffff0000, v137
	v_pk_mul_f32 v[14:15], v[14:15], v[200:201]
	v_lshlrev_b32_e32 v194, 16, v166
	v_and_b32_e32 v195, 0xffff0000, v166
	v_pk_add_f32 v[48:49], v[48:49], v[194:195]
	v_lshlrev_b32_e32 v196, 16, v167
	v_and_b32_e32 v197, 0xffff0000, v167
	v_pk_add_f32 v[50:51], v[50:51], v[196:197]
	v_lshlrev_b32_e32 v198, 16, v168
	v_and_b32_e32 v199, 0xffff0000, v168
	v_pk_add_f32 v[12:13], v[12:13], v[198:199]
	v_lshlrev_b32_e32 v200, 16, v169
	v_and_b32_e32 v201, 0xffff0000, v169
	v_pk_add_f32 v[14:15], v[14:15], v[200:201]
	v_cvt_pk_bf16_f32 v48, v48, v49
	v_cvt_pk_bf16_f32 v49, v50, v51
	v_cvt_pk_bf16_f32 v50, v12, v13
	v_cvt_pk_bf16_f32 v51, v14, v15
	v_lshlrev_b32_e32 v194, 16, v138
	v_and_b32_e32 v195, 0xffff0000, v138
	v_pk_mul_f32 v[122:123], v[122:123], v[194:195]
	v_lshlrev_b32_e32 v196, 16, v139
	v_and_b32_e32 v197, 0xffff0000, v139
	v_pk_mul_f32 v[124:125], v[124:125], v[196:197]
	v_lshlrev_b32_e32 v198, 16, v140
	v_and_b32_e32 v199, 0xffff0000, v140
	v_pk_mul_f32 v[118:119], v[118:119], v[198:199]
	v_lshlrev_b32_e32 v200, 16, v141
	v_and_b32_e32 v201, 0xffff0000, v141
	v_pk_mul_f32 v[120:121], v[120:121], v[200:201]
	v_lshlrev_b32_e32 v194, 16, v170
	v_and_b32_e32 v195, 0xffff0000, v170
	v_pk_add_f32 v[122:123], v[122:123], v[194:195]
; __device__ __forceinline__ unsigned pk2(float lo, float hi) { unsigned r; asm volatile("v_cvt_pk_bf16_f32 %0, %1, %2" : "=v"(r) : "v"(lo), "v"(hi)); return r; }
; __device__ __forceinline__ float bflo(unsigned w) { return __uint_as_float(w << 16); }
; __device__ __forceinline__ float bfhi(unsigned w) { return __uint_as_float(w & 0xffff0000u); }
; #define GAS __attribute__((address_space(1)))
; __device__ __forceinline__ void gemm_epilogue(LAS unsigned char* lds, const GD& gd, const f32x4 (&acc)[2][2][4][2], const Unit& u) {
;     ...
;     if (mode == M_YSET || mode == M_YADD) {
; #pragma unroll
;         for (int am = 0; am < 8 / MBG; ++am) {
;             const int ai = (am * MBG) >> 2, m0 = (am * MBG) & 3;
;             u32x4 gw[MBG][2], yw[MBG][2];
; #pragma unroll
;             for (int mm = 0; mm < MBG; ++mm)
; #pragma unroll
;                 for (int bj = 0; bj < 2; ++bj) {
;                     const int ro = ai * HALF + (m0 + mm) * 16;
;                     gw[mm][bj] = *(GAS const u32x4*)(auxu + goff + ro * apitch + bj * HALF);
;                     if (mode == M_YADD) yw[mm][bj] = *(GAS const u32x4*)(outu + ooff + ro * ldc + bj * HALF);
;                 }
;             asm volatile("" ::: "memory");
; #pragma unroll
;             for (int mm = 0; mm < MBG; ++mm) {
;                 const int m = m0 + mm;
; #pragma unroll
;                 for (int bj = 0; bj < 2; ++bj) {
;                     f32x4 v0 = acc[ai][bj][m][0], v1 = acc[ai][bj][m][1];
;                     const u32x4 q = gw[mm][bj];
;                     v0[0] *= bflo(q.x); v0[1] *= bfhi(q.x); v0[2] *= bflo(q.y); v0[3] *= bfhi(q.y);
;                     v1[0] *= bflo(q.z); v1[1] *= bfhi(q.z); v1[2] *= bflo(q.w); v1[3] *= bfhi(q.w);
;                     if (mode == M_YADD) {
;                         const u32x4 y = yw[mm][bj];
;                         v0[0] += bflo(y.x); v0[1] += bfhi(y.x); v0[2] += bflo(y.y); v0[3] += bfhi(y.y);
;                         v1[0] += bflo(y.z); v1[1] += bfhi(y.z); v1[2] += bflo(y.w); v1[3] += bfhi(y.w);
;                     }
;                     u32x4 w; w.x = pk2(v0[0], v0[1]); w.y = pk2(v0[2], v0[3]); w.z = pk2(v1[0], v1[1]); w.w = pk2(v1[2], v1[3]);
;                     *(GAS u32x4*)(outu + ooff + (ai * HALF + m * 16) * ldc + bj * HALF) = w;
;                 }
;             }
;         }
;         return;
;     }
	v_lshlrev_b32_e32 v196, 16, v171
	v_and_b32_e32 v197, 0xffff0000, v171
	v_pk_add_f32 v[124:125], v[124:125], v[196:197]
	v_lshlrev_b32_e32 v198, 16, v172
	v_and_b32_e32 v199, 0xffff0000, v172
	v_pk_add_f32 v[118:119], v[118:119], v[198:199]
	v_lshlrev_b32_e32 v200, 16, v173
	v_and_b32_e32 v201, 0xffff0000, v173
	v_pk_add_f32 v[120:121], v[120:121], v[200:201]
	v_cvt_pk_bf16_f32 v122, v122, v123
	v_cvt_pk_bf16_f32 v123, v124, v125
	v_cvt_pk_bf16_f32 v124, v118, v119
	v_cvt_pk_bf16_f32 v125, v120, v121
	v_lshlrev_b32_e32 v194, 16, v142
	v_and_b32_e32 v195, 0xffff0000, v142
	v_pk_mul_f32 v[102:103], v[102:103], v[194:195]
	v_lshlrev_b32_e32 v196, 16, v143
	v_and_b32_e32 v197, 0xffff0000, v143
	v_pk_mul_f32 v[104:105], v[104:105], v[196:197]
	v_lshlrev_b32_e32 v198, 16, v144
	v_and_b32_e32 v199, 0xffff0000, v144
	v_pk_mul_f32 v[98:99], v[98:99], v[198:199]
	v_lshlrev_b32_e32 v200, 16, v145
	v_and_b32_e32 v201, 0xffff0000, v145
	v_pk_mul_f32 v[100:101], v[100:101], v[200:201]
	v_lshlrev_b32_e32 v194, 16, v174
	v_and_b32_e32 v195, 0xffff0000, v174
	v_pk_add_f32 v[102:103], v[102:103], v[194:195]
	v_lshlrev_b32_e32 v196, 16, v175
	v_and_b32_e32 v197, 0xffff0000, v175
	v_pk_add_f32 v[104:105], v[104:105], v[196:197]
	v_lshlrev_b32_e32 v198, 16, v176
	v_and_b32_e32 v199, 0xffff0000, v176
	v_pk_add_f32 v[98:99], v[98:99], v[198:199]
	v_lshlrev_b32_e32 v200, 16, v177
	v_and_b32_e32 v201, 0xffff0000, v177
	v_pk_add_f32 v[100:101], v[100:101], v[200:201]
	v_cvt_pk_bf16_f32 v102, v102, v103
	v_cvt_pk_bf16_f32 v103, v104, v105
	v_cvt_pk_bf16_f32 v104, v98, v99
	v_cvt_pk_bf16_f32 v105, v100, v101
	v_lshlrev_b32_e32 v194, 16, v146
	v_and_b32_e32 v195, 0xffff0000, v146
	v_pk_mul_f32 v[114:115], v[114:115], v[194:195]
	v_lshlrev_b32_e32 v196, 16, v147
	v_and_b32_e32 v197, 0xffff0000, v147
	v_pk_mul_f32 v[116:117], v[116:117], v[196:197]
	v_lshlrev_b32_e32 v198, 16, v148
	v_and_b32_e32 v199, 0xffff0000, v148
	v_pk_mul_f32 v[110:111], v[110:111], v[198:199]
	v_lshlrev_b32_e32 v200, 16, v149
	v_and_b32_e32 v201, 0xffff0000, v149
	v_pk_mul_f32 v[112:113], v[112:113], v[200:201]
	v_lshlrev_b32_e32 v194, 16, v178
	v_and_b32_e32 v195, 0xffff0000, v178
	v_pk_add_f32 v[114:115], v[114:115], v[194:195]
	v_lshlrev_b32_e32 v196, 16, v179
	v_and_b32_e32 v197, 0xffff0000, v179
	v_pk_add_f32 v[116:117], v[116:117], v[196:197]
	v_lshlrev_b32_e32 v198, 16, v180
	v_and_b32_e32 v199, 0xffff0000, v180
	v_pk_add_f32 v[110:111], v[110:111], v[198:199]
	v_lshlrev_b32_e32 v200, 16, v181
	v_and_b32_e32 v201, 0xffff0000, v181
	v_pk_add_f32 v[112:113], v[112:113], v[200:201]
	v_cvt_pk_bf16_f32 v114, v114, v115
	v_cvt_pk_bf16_f32 v115, v116, v117
	v_cvt_pk_bf16_f32 v116, v110, v111
	v_cvt_pk_bf16_f32 v117, v112, v113
	v_lshlrev_b32_e32 v194, 16, v150
	v_and_b32_e32 v195, 0xffff0000, v150
	v_pk_mul_f32 v[92:93], v[92:93], v[194:195]
	v_lshlrev_b32_e32 v196, 16, v151
	v_and_b32_e32 v197, 0xffff0000, v151
	v_pk_mul_f32 v[94:95], v[94:95], v[196:197]
	v_lshlrev_b32_e32 v198, 16, v152
	v_and_b32_e32 v199, 0xffff0000, v152
	v_pk_mul_f32 v[88:89], v[88:89], v[198:199]
	v_lshlrev_b32_e32 v200, 16, v153
	v_and_b32_e32 v201, 0xffff0000, v153
	v_pk_mul_f32 v[90:91], v[90:91], v[200:201]
	v_lshlrev_b32_e32 v194, 16, v182
	v_and_b32_e32 v195, 0xffff0000, v182
	v_pk_add_f32 v[92:93], v[92:93], v[194:195]
	v_lshlrev_b32_e32 v196, 16, v183
	v_and_b32_e32 v197, 0xffff0000, v183
	v_pk_add_f32 v[94:95], v[94:95], v[196:197]
	v_lshlrev_b32_e32 v198, 16, v184
	v_and_b32_e32 v199, 0xffff0000, v184
	v_pk_add_f32 v[88:89], v[88:89], v[198:199]
	v_lshlrev_b32_e32 v200, 16, v185
	v_and_b32_e32 v201, 0xffff0000, v185
	v_pk_add_f32 v[90:91], v[90:91], v[200:201]
	v_cvt_pk_bf16_f32 v92, v92, v93
	v_cvt_pk_bf16_f32 v93, v94, v95
	v_cvt_pk_bf16_f32 v94, v88, v89
	v_cvt_pk_bf16_f32 v95, v90, v91
	v_lshlrev_b32_e32 v194, 16, v154
	v_and_b32_e32 v195, 0xffff0000, v154
	v_pk_mul_f32 v[106:107], v[106:107], v[194:195]
	v_lshlrev_b32_e32 v196, 16, v155
	v_and_b32_e32 v197, 0xffff0000, v155
	v_pk_mul_f32 v[108:109], v[108:109], v[196:197]
	v_lshlrev_b32_e32 v198, 16, v156
	v_and_b32_e32 v199, 0xffff0000, v156
	v_pk_mul_f32 v[8:9], v[8:9], v[198:199]
	v_lshlrev_b32_e32 v200, 16, v157
	v_and_b32_e32 v201, 0xffff0000, v157
	v_pk_mul_f32 v[10:11], v[10:11], v[200:201]
	v_lshlrev_b32_e32 v194, 16, v186
	v_and_b32_e32 v195, 0xffff0000, v186
	v_pk_add_f32 v[106:107], v[106:107], v[194:195]
	v_lshlrev_b32_e32 v196, 16, v187
	v_and_b32_e32 v197, 0xffff0000, v187
	v_pk_add_f32 v[108:109], v[108:109], v[196:197]
	v_lshlrev_b32_e32 v198, 16, v188
	v_and_b32_e32 v199, 0xffff0000, v188
	v_pk_add_f32 v[8:9], v[8:9], v[198:199]
	v_lshlrev_b32_e32 v200, 16, v189
	v_and_b32_e32 v201, 0xffff0000, v189
	v_pk_add_f32 v[10:11], v[10:11], v[200:201]
	v_cvt_pk_bf16_f32 v106, v106, v107
	v_cvt_pk_bf16_f32 v107, v108, v109
	v_cvt_pk_bf16_f32 v108, v8, v9
	v_cvt_pk_bf16_f32 v109, v10, v11
	v_lshlrev_b32_e32 v194, 16, v158
	v_and_b32_e32 v195, 0xffff0000, v158
	v_pk_mul_f32 v[44:45], v[44:45], v[194:195]
	v_lshlrev_b32_e32 v196, 16, v159
	v_and_b32_e32 v197, 0xffff0000, v159
	v_pk_mul_f32 v[46:47], v[46:47], v[196:197]
	v_lshlrev_b32_e32 v198, 16, v160
	v_and_b32_e32 v199, 0xffff0000, v160
	v_pk_mul_f32 v[16:17], v[16:17], v[198:199]
	v_lshlrev_b32_e32 v200, 16, v161
	v_and_b32_e32 v201, 0xffff0000, v161
	v_pk_mul_f32 v[18:19], v[18:19], v[200:201]
	v_lshlrev_b32_e32 v194, 16, v190
	v_and_b32_e32 v195, 0xffff0000, v190
	v_pk_add_f32 v[44:45], v[44:45], v[194:195]
	v_lshlrev_b32_e32 v196, 16, v191
	v_and_b32_e32 v197, 0xffff0000, v191
	v_pk_add_f32 v[46:47], v[46:47], v[196:197]
	v_lshlrev_b32_e32 v198, 16, v192
	v_and_b32_e32 v199, 0xffff0000, v192
; __device__ __forceinline__ unsigned pk2(float lo, float hi) { unsigned r; asm volatile("v_cvt_pk_bf16_f32 %0, %1, %2" : "=v"(r) : "v"(lo), "v"(hi)); return r; }
; __device__ __forceinline__ float bflo(unsigned w) { return __uint_as_float(w << 16); }
; __device__ __forceinline__ float bfhi(unsigned w) { return __uint_as_float(w & 0xffff0000u); }
; #define GAS __attribute__((address_space(1)))
; __device__ __forceinline__ void gemm_epilogue(LAS unsigned char* lds, const GD& gd, const f32x4 (&acc)[2][2][4][2], const Unit& u) {
;     ...
;     if (mode == M_YSET || mode == M_YADD) {
; #pragma unroll
;         for (int am = 0; am < 8 / MBG; ++am) {
;             const int ai = (am * MBG) >> 2, m0 = (am * MBG) & 3;
;             u32x4 gw[MBG][2], yw[MBG][2];
; #pragma unroll
;             for (int mm = 0; mm < MBG; ++mm)
; #pragma unroll
;                 for (int bj = 0; bj < 2; ++bj) {
;                     const int ro = ai * HALF + (m0 + mm) * 16;
;                     gw[mm][bj] = *(GAS const u32x4*)(auxu + goff + ro * apitch + bj * HALF);
;                     if (mode == M_YADD) yw[mm][bj] = *(GAS const u32x4*)(outu + ooff + ro * ldc + bj * HALF);
;                 }
;             asm volatile("" ::: "memory");
; #pragma unroll
;             for (int mm = 0; mm < MBG; ++mm) {
;                 const int m = m0 + mm;
; #pragma unroll
;                 for (int bj = 0; bj < 2; ++bj) {
;                     f32x4 v0 = acc[ai][bj][m][0], v1 = acc[ai][bj][m][1];
;                     const u32x4 q = gw[mm][bj];
;                     v0[0] *= bflo(q.x); v0[1] *= bfhi(q.x); v0[2] *= bflo(q.y); v0[3] *= bfhi(q.y);
;                     v1[0] *= bflo(q.z); v1[1] *= bfhi(q.z); v1[2] *= bflo(q.w); v1[3] *= bfhi(q.w);
;                     if (mode == M_YADD) {
;                         const u32x4 y = yw[mm][bj];
;                         v0[0] += bflo(y.x); v0[1] += bfhi(y.x); v0[2] += bflo(y.y); v0[3] += bfhi(y.y);
;                         v1[0] += bflo(y.z); v1[1] += bfhi(y.z); v1[2] += bflo(y.w); v1[3] += bfhi(y.w);
;                     }
;                     u32x4 w; w.x = pk2(v0[0], v0[1]); w.y = pk2(v0[2], v0[3]); w.z = pk2(v1[0], v1[1]); w.w = pk2(v1[2], v1[3]);
;                     *(GAS u32x4*)(outu + ooff + (ai * HALF + m * 16) * ldc + bj * HALF) = w;
;                 }
;             }
;         }
;         return;
;     }
	v_pk_add_f32 v[16:17], v[16:17], v[198:199]
	v_lshlrev_b32_e32 v200, 16, v193
	v_and_b32_e32 v201, 0xffff0000, v193
	v_pk_add_f32 v[18:19], v[18:19], v[200:201]
	v_cvt_pk_bf16_f32 v44, v44, v45
	v_cvt_pk_bf16_f32 v45, v46, v47
	v_cvt_pk_bf16_f32 v46, v16, v17
	v_cvt_pk_bf16_f32 v47, v18, v19
	global_load_dwordx4 v[130:133], v202, s[46:47]
	global_load_dwordx4 v[134:137], v202, s[46:47] offset:256
	global_load_dwordx4 v[162:165], v203, s[48:49]
	global_load_dwordx4 v[166:169], v203, s[48:49] offset:256
	s_add_u32 s46, s46, s2
	s_addc_u32 s47, s47, 0
	s_add_u32 s48, s48, s7
	s_addc_u32 s49, s49, 0
	global_load_dwordx4 v[138:141], v202, s[46:47]
	global_load_dwordx4 v[142:145], v202, s[46:47] offset:256
	global_load_dwordx4 v[170:173], v203, s[48:49]
	global_load_dwordx4 v[174:177], v203, s[48:49] offset:256
	s_add_u32 s46, s46, s2
	s_addc_u32 s47, s47, 0
	s_add_u32 s48, s48, s7
	s_addc_u32 s49, s49, 0
	global_load_dwordx4 v[146:149], v202, s[46:47]
	global_load_dwordx4 v[150:153], v202, s[46:47] offset:256
	global_load_dwordx4 v[178:181], v203, s[48:49]
	global_load_dwordx4 v[182:185], v203, s[48:49] offset:256
	s_add_u32 s46, s46, s2
	s_addc_u32 s47, s47, 0
	s_add_u32 s48, s48, s7
	s_addc_u32 s49, s49, 0
	global_load_dwordx4 v[154:157], v202, s[46:47]
	global_load_dwordx4 v[158:161], v202, s[46:47] offset:256
	global_load_dwordx4 v[186:189], v203, s[48:49]
	global_load_dwordx4 v[190:193], v203, s[48:49] offset:256
	s_add_u32 s46, s46, s2
	s_addc_u32 s47, s47, 0
	s_add_u32 s48, s48, s7
	s_addc_u32 s49, s49, 0
	global_store_dwordx4 v203, v[126:129], s[50:51]
	global_store_dwordx4 v203, v[48:51], s[50:51] offset:256
	s_add_u32 s50, s50, s7
	s_addc_u32 s51, s51, 0
	global_store_dwordx4 v203, v[122:125], s[50:51]
	global_store_dwordx4 v203, v[102:105], s[50:51] offset:256
	s_add_u32 s50, s50, s7
	s_addc_u32 s51, s51, 0
	global_store_dwordx4 v203, v[114:117], s[50:51]
	global_store_dwordx4 v203, v[92:95], s[50:51] offset:256
	s_add_u32 s50, s50, s7
	s_addc_u32 s51, s51, 0
	global_store_dwordx4 v203, v[106:109], s[50:51]
	global_store_dwordx4 v203, v[44:47], s[50:51] offset:256
	s_add_u32 s50, s50, s7
	s_addc_u32 s51, s51, 0
	s_add_u32 s50, s50, s45
	s_addc_u32 s51, s51, 0
	s_waitcnt vmcnt(8)
	v_lshlrev_b32_e32 v194, 16, v130
	v_and_b32_e32 v195, 0xffff0000, v130
	v_pk_mul_f32 v[84:85], v[84:85], v[194:195]
	v_lshlrev_b32_e32 v196, 16, v131
	v_and_b32_e32 v197, 0xffff0000, v131
	v_pk_mul_f32 v[86:87], v[86:87], v[196:197]
	v_lshlrev_b32_e32 v198, 16, v132
	v_and_b32_e32 v199, 0xffff0000, v132
	v_pk_mul_f32 v[20:21], v[20:21], v[198:199]
	v_lshlrev_b32_e32 v200, 16, v133
	v_and_b32_e32 v201, 0xffff0000, v133
	v_pk_mul_f32 v[22:23], v[22:23], v[200:201]
	v_lshlrev_b32_e32 v194, 16, v162
	v_and_b32_e32 v195, 0xffff0000, v162
	v_pk_add_f32 v[84:85], v[84:85], v[194:195]
	v_lshlrev_b32_e32 v196, 16, v163
	v_and_b32_e32 v197, 0xffff0000, v163
	v_pk_add_f32 v[86:87], v[86:87], v[196:197]
	v_lshlrev_b32_e32 v198, 16, v164
	v_and_b32_e32 v199, 0xffff0000, v164
	v_pk_add_f32 v[20:21], v[20:21], v[198:199]
	v_lshlrev_b32_e32 v200, 16, v165
	v_and_b32_e32 v201, 0xffff0000, v165
	v_pk_add_f32 v[22:23], v[22:23], v[200:201]
	v_cvt_pk_bf16_f32 v84, v84, v85
	v_cvt_pk_bf16_f32 v85, v86, v87
	v_cvt_pk_bf16_f32 v86, v20, v21
	v_cvt_pk_bf16_f32 v87, v22, v23
	v_lshlrev_b32_e32 v194, 16, v134
	v_and_b32_e32 v195, 0xffff0000, v134
	v_pk_mul_f32 v[40:41], v[40:41], v[194:195]
	v_lshlrev_b32_e32 v196, 16, v135
	v_and_b32_e32 v197, 0xffff0000, v135
	v_pk_mul_f32 v[42:43], v[42:43], v[196:197]
	v_lshlrev_b32_e32 v198, 16, v136
	v_and_b32_e32 v199, 0xffff0000, v136
	v_pk_mul_f32 v[28:29], v[28:29], v[198:199]
	v_lshlrev_b32_e32 v200, 16, v137
	v_and_b32_e32 v201, 0xffff0000, v137
	v_pk_mul_f32 v[30:31], v[30:31], v[200:201]
	v_lshlrev_b32_e32 v194, 16, v166
	v_and_b32_e32 v195, 0xffff0000, v166
	v_pk_add_f32 v[40:41], v[40:41], v[194:195]
	v_lshlrev_b32_e32 v196, 16, v167
	v_and_b32_e32 v197, 0xffff0000, v167
	v_pk_add_f32 v[42:43], v[42:43], v[196:197]
	v_lshlrev_b32_e32 v198, 16, v168
	v_and_b32_e32 v199, 0xffff0000, v168
	v_pk_add_f32 v[28:29], v[28:29], v[198:199]
	v_lshlrev_b32_e32 v200, 16, v169
	v_and_b32_e32 v201, 0xffff0000, v169
	v_pk_add_f32 v[30:31], v[30:31], v[200:201]
	v_cvt_pk_bf16_f32 v40, v40, v41
	v_cvt_pk_bf16_f32 v41, v42, v43
	v_cvt_pk_bf16_f32 v42, v28, v29
	v_cvt_pk_bf16_f32 v43, v30, v31
	v_lshlrev_b32_e32 v194, 16, v138
	v_and_b32_e32 v195, 0xffff0000, v138
	v_pk_mul_f32 v[80:81], v[80:81], v[194:195]
	v_lshlrev_b32_e32 v196, 16, v139
	v_and_b32_e32 v197, 0xffff0000, v139
	v_pk_mul_f32 v[82:83], v[82:83], v[196:197]
	v_lshlrev_b32_e32 v198, 16, v140
	v_and_b32_e32 v199, 0xffff0000, v140
	v_pk_mul_f32 v[76:77], v[76:77], v[198:199]
	v_lshlrev_b32_e32 v200, 16, v141
	v_and_b32_e32 v201, 0xffff0000, v141
	v_pk_mul_f32 v[78:79], v[78:79], v[200:201]
	v_lshlrev_b32_e32 v194, 16, v170
	v_and_b32_e32 v195, 0xffff0000, v170
	v_pk_add_f32 v[80:81], v[80:81], v[194:195]
	v_lshlrev_b32_e32 v196, 16, v171
	v_and_b32_e32 v197, 0xffff0000, v171
	v_pk_add_f32 v[82:83], v[82:83], v[196:197]
	v_lshlrev_b32_e32 v198, 16, v172
	v_and_b32_e32 v199, 0xffff0000, v172
	v_pk_add_f32 v[76:77], v[76:77], v[198:199]
	v_lshlrev_b32_e32 v200, 16, v173
	v_and_b32_e32 v201, 0xffff0000, v173
	v_pk_add_f32 v[78:79], v[78:79], v[200:201]
	v_cvt_pk_bf16_f32 v80, v80, v81
	v_cvt_pk_bf16_f32 v81, v82, v83
	v_cvt_pk_bf16_f32 v82, v76, v77
	v_cvt_pk_bf16_f32 v83, v78, v79
	v_lshlrev_b32_e32 v194, 16, v142
	v_and_b32_e32 v195, 0xffff0000, v142
	v_pk_mul_f32 v[60:61], v[60:61], v[194:195]
	v_lshlrev_b32_e32 v196, 16, v143
	v_and_b32_e32 v197, 0xffff0000, v143
; __device__ __forceinline__ unsigned pk2(float lo, float hi) { unsigned r; asm volatile("v_cvt_pk_bf16_f32 %0, %1, %2" : "=v"(r) : "v"(lo), "v"(hi)); return r; }
; __device__ __forceinline__ float bflo(unsigned w) { return __uint_as_float(w << 16); }
; __device__ __forceinline__ float bfhi(unsigned w) { return __uint_as_float(w & 0xffff0000u); }
; #define GAS __attribute__((address_space(1)))
; __device__ __forceinline__ void gemm_epilogue(LAS unsigned char* lds, const GD& gd, const f32x4 (&acc)[2][2][4][2], const Unit& u) {
;     ...
;     if (mode == M_YSET || mode == M_YADD) {
; #pragma unroll
;         for (int am = 0; am < 8 / MBG; ++am) {
;             const int ai = (am * MBG) >> 2, m0 = (am * MBG) & 3;
;             u32x4 gw[MBG][2], yw[MBG][2];
; #pragma unroll
;             for (int mm = 0; mm < MBG; ++mm)
; #pragma unroll
;                 for (int bj = 0; bj < 2; ++bj) {
;                     const int ro = ai * HALF + (m0 + mm) * 16;
;                     gw[mm][bj] = *(GAS const u32x4*)(auxu + goff + ro * apitch + bj * HALF);
;                     if (mode == M_YADD) yw[mm][bj] = *(GAS const u32x4*)(outu + ooff + ro * ldc + bj * HALF);
;                 }
;             asm volatile("" ::: "memory");
; #pragma unroll
;             for (int mm = 0; mm < MBG; ++mm) {
;                 const int m = m0 + mm;
; #pragma unroll
;                 for (int bj = 0; bj < 2; ++bj) {
;                     f32x4 v0 = acc[ai][bj][m][0], v1 = acc[ai][bj][m][1];
;                     const u32x4 q = gw[mm][bj];
;                     v0[0] *= bflo(q.x); v0[1] *= bfhi(q.x); v0[2] *= bflo(q.y); v0[3] *= bfhi(q.y);
;                     v1[0] *= bflo(q.z); v1[1] *= bfhi(q.z); v1[2] *= bflo(q.w); v1[3] *= bfhi(q.w);
;                     if (mode == M_YADD) {
;                         const u32x4 y = yw[mm][bj];
;                         v0[0] += bflo(y.x); v0[1] += bfhi(y.x); v0[2] += bflo(y.y); v0[3] += bfhi(y.y);
;                         v1[0] += bflo(y.z); v1[1] += bfhi(y.z); v1[2] += bflo(y.w); v1[3] += bfhi(y.w);
;                     }
;                     u32x4 w; w.x = pk2(v0[0], v0[1]); w.y = pk2(v0[2], v0[3]); w.z = pk2(v1[0], v1[1]); w.w = pk2(v1[2], v1[3]);
;                     *(GAS u32x4*)(outu + ooff + (ai * HALF + m * 16) * ldc + bj * HALF) = w;
;                 }
;             }
;         }
;         return;
;     }
	v_pk_mul_f32 v[62:63], v[62:63], v[196:197]
	v_lshlrev_b32_e32 v198, 16, v144
	v_and_b32_e32 v199, 0xffff0000, v144
	v_pk_mul_f32 v[56:57], v[56:57], v[198:199]
	v_lshlrev_b32_e32 v200, 16, v145
	v_and_b32_e32 v201, 0xffff0000, v145
	v_pk_mul_f32 v[58:59], v[58:59], v[200:201]
	v_lshlrev_b32_e32 v194, 16, v174
	v_and_b32_e32 v195, 0xffff0000, v174
	v_pk_add_f32 v[60:61], v[60:61], v[194:195]
	v_lshlrev_b32_e32 v196, 16, v175
	v_and_b32_e32 v197, 0xffff0000, v175
	v_pk_add_f32 v[62:63], v[62:63], v[196:197]
	v_lshlrev_b32_e32 v198, 16, v176
	v_and_b32_e32 v199, 0xffff0000, v176
	v_pk_add_f32 v[56:57], v[56:57], v[198:199]
	v_lshlrev_b32_e32 v200, 16, v177
	v_and_b32_e32 v201, 0xffff0000, v177
	v_pk_add_f32 v[58:59], v[58:59], v[200:201]
	v_cvt_pk_bf16_f32 v60, v60, v61
	v_cvt_pk_bf16_f32 v61, v62, v63
	v_cvt_pk_bf16_f32 v62, v56, v57
	v_cvt_pk_bf16_f32 v63, v58, v59
	v_lshlrev_b32_e32 v194, 16, v146
	v_and_b32_e32 v195, 0xffff0000, v146
	v_pk_mul_f32 v[72:73], v[72:73], v[194:195]
	v_lshlrev_b32_e32 v196, 16, v147
	v_and_b32_e32 v197, 0xffff0000, v147
	v_pk_mul_f32 v[74:75], v[74:75], v[196:197]
	v_lshlrev_b32_e32 v198, 16, v148
	v_and_b32_e32 v199, 0xffff0000, v148
	v_pk_mul_f32 v[68:69], v[68:69], v[198:199]
	v_lshlrev_b32_e32 v200, 16, v149
	v_and_b32_e32 v201, 0xffff0000, v149
	v_pk_mul_f32 v[70:71], v[70:71], v[200:201]
	v_lshlrev_b32_e32 v194, 16, v178
	v_and_b32_e32 v195, 0xffff0000, v178
	v_pk_add_f32 v[72:73], v[72:73], v[194:195]
	v_lshlrev_b32_e32 v196, 16, v179
	v_and_b32_e32 v197, 0xffff0000, v179
	v_pk_add_f32 v[74:75], v[74:75], v[196:197]
	v_lshlrev_b32_e32 v198, 16, v180
	v_and_b32_e32 v199, 0xffff0000, v180
	v_pk_add_f32 v[68:69], v[68:69], v[198:199]
	v_lshlrev_b32_e32 v200, 16, v181
	v_and_b32_e32 v201, 0xffff0000, v181
	v_pk_add_f32 v[70:71], v[70:71], v[200:201]
	v_cvt_pk_bf16_f32 v72, v72, v73
	v_cvt_pk_bf16_f32 v73, v74, v75
	v_cvt_pk_bf16_f32 v74, v68, v69
	v_cvt_pk_bf16_f32 v75, v70, v71
	v_lshlrev_b32_e32 v194, 16, v150
	v_and_b32_e32 v195, 0xffff0000, v150
	v_pk_mul_f32 v[52:53], v[52:53], v[194:195]
	v_lshlrev_b32_e32 v196, 16, v151
	v_and_b32_e32 v197, 0xffff0000, v151
	v_pk_mul_f32 v[54:55], v[54:55], v[196:197]
	v_lshlrev_b32_e32 v198, 16, v152
	v_and_b32_e32 v199, 0xffff0000, v152
	v_pk_mul_f32 v[0:1], v[0:1], v[198:199]
	v_lshlrev_b32_e32 v200, 16, v153
	v_and_b32_e32 v201, 0xffff0000, v153
	v_pk_mul_f32 v[2:3], v[2:3], v[200:201]
	v_lshlrev_b32_e32 v194, 16, v182
	v_and_b32_e32 v195, 0xffff0000, v182
	v_pk_add_f32 v[52:53], v[52:53], v[194:195]
	v_lshlrev_b32_e32 v196, 16, v183
	v_and_b32_e32 v197, 0xffff0000, v183
	v_pk_add_f32 v[54:55], v[54:55], v[196:197]
	v_lshlrev_b32_e32 v198, 16, v184
	v_and_b32_e32 v199, 0xffff0000, v184
	v_pk_add_f32 v[0:1], v[0:1], v[198:199]
	v_lshlrev_b32_e32 v200, 16, v185
	v_and_b32_e32 v201, 0xffff0000, v185
	v_pk_add_f32 v[2:3], v[2:3], v[200:201]
	v_cvt_pk_bf16_f32 v52, v52, v53
	v_cvt_pk_bf16_f32 v53, v54, v55
	v_cvt_pk_bf16_f32 v54, v0, v1
	v_cvt_pk_bf16_f32 v55, v2, v3
	v_lshlrev_b32_e32 v194, 16, v154
	v_and_b32_e32 v195, 0xffff0000, v154
	v_pk_mul_f32 v[64:65], v[64:65], v[194:195]
	v_lshlrev_b32_e32 v196, 16, v155
	v_and_b32_e32 v197, 0xffff0000, v155
	v_pk_mul_f32 v[66:67], v[66:67], v[196:197]
	v_lshlrev_b32_e32 v198, 16, v156
	v_and_b32_e32 v199, 0xffff0000, v156
	v_pk_mul_f32 v[24:25], v[24:25], v[198:199]
	v_lshlrev_b32_e32 v200, 16, v157
	v_and_b32_e32 v201, 0xffff0000, v157
	v_pk_mul_f32 v[26:27], v[26:27], v[200:201]
	v_lshlrev_b32_e32 v194, 16, v186
	v_and_b32_e32 v195, 0xffff0000, v186
	v_pk_add_f32 v[64:65], v[64:65], v[194:195]
	v_lshlrev_b32_e32 v196, 16, v187
	v_and_b32_e32 v197, 0xffff0000, v187
	v_pk_add_f32 v[66:67], v[66:67], v[196:197]
	v_lshlrev_b32_e32 v198, 16, v188
	v_and_b32_e32 v199, 0xffff0000, v188
	v_pk_add_f32 v[24:25], v[24:25], v[198:199]
	v_lshlrev_b32_e32 v200, 16, v189
	v_and_b32_e32 v201, 0xffff0000, v189
	v_pk_add_f32 v[26:27], v[26:27], v[200:201]
	v_cvt_pk_bf16_f32 v64, v64, v65
	v_cvt_pk_bf16_f32 v65, v66, v67
	v_cvt_pk_bf16_f32 v66, v24, v25
	v_cvt_pk_bf16_f32 v67, v26, v27
	v_lshlrev_b32_e32 v194, 16, v158
	v_and_b32_e32 v195, 0xffff0000, v158
	v_pk_mul_f32 v[36:37], v[36:37], v[194:195]
	v_lshlrev_b32_e32 v196, 16, v159
	v_and_b32_e32 v197, 0xffff0000, v159
	v_pk_mul_f32 v[38:39], v[38:39], v[196:197]
	v_lshlrev_b32_e32 v198, 16, v160
	v_and_b32_e32 v199, 0xffff0000, v160
	v_pk_mul_f32 v[32:33], v[32:33], v[198:199]
	v_lshlrev_b32_e32 v200, 16, v161
	v_and_b32_e32 v201, 0xffff0000, v161
	v_pk_mul_f32 v[34:35], v[34:35], v[200:201]
	v_lshlrev_b32_e32 v194, 16, v190
	v_and_b32_e32 v195, 0xffff0000, v190
	v_pk_add_f32 v[36:37], v[36:37], v[194:195]
	v_lshlrev_b32_e32 v196, 16, v191
	v_and_b32_e32 v197, 0xffff0000, v191
	v_pk_add_f32 v[38:39], v[38:39], v[196:197]
	v_lshlrev_b32_e32 v198, 16, v192
	v_and_b32_e32 v199, 0xffff0000, v192
	v_pk_add_f32 v[32:33], v[32:33], v[198:199]
	v_lshlrev_b32_e32 v200, 16, v193
	v_and_b32_e32 v201, 0xffff0000, v193
	v_pk_add_f32 v[34:35], v[34:35], v[200:201]
	v_cvt_pk_bf16_f32 v36, v36, v37
	v_cvt_pk_bf16_f32 v37, v38, v39
	v_cvt_pk_bf16_f32 v38, v32, v33
	v_cvt_pk_bf16_f32 v39, v34, v35
	global_store_dwordx4 v203, v[84:87], s[50:51]
	global_store_dwordx4 v203, v[40:43], s[50:51] offset:256
	s_add_u32 s50, s50, s7
	s_addc_u32 s51, s51, 0
	global_store_dwordx4 v203, v[80:83], s[50:51]
	global_store_dwordx4 v203, v[60:63], s[50:51] offset:256
	s_add_u32 s50, s50, s7
	s_addc_u32 s51, s51, 0
	global_store_dwordx4 v203, v[72:75], s[50:51]
	global_store_dwordx4 v203, v[52:55], s[50:51] offset:256
	s_add_u32 s50, s50, s7
	s_addc_u32 s51, s51, 0
	global_store_dwordx4 v203, v[64:67], s[50:51]
	global_store_dwordx4 v203, v[36:39], s[50:51] offset:256
	s_add_u32 s50, s50, s7
	s_addc_u32 s51, s51, 0
